# speedup vs baseline: 1.0038x; 1.0038x over previous
; #define WAIT_V0() asm volatile("s_waitcnt vmcnt(0)" ::: "memory")
; template <int MT, class Epi>
; DEV void gemm_tile(char* shm, const u16* __restrict__ Ab, const u16* __restrict__ Bb, int K, int brow, int bcol, Epi& epi) {
;     ...
;   GLDS_STAGE_(0, 0);
;   WAIT_V0();
;   __syncthreads();
; #pragma unroll 1
;   for (int t = 0; t < nt; ++t) {
;     const int cur = t & 1;
;     if (t + 1 < nt) GLDS_STAGE_(cur ^ 1, t + 1);
;     {
;       bf16x8 At[MT], Bf0[4], Bf1[4];
; #pragma unroll
;       for (int m = 0; m < MT; ++m) At[m] = *(const bf16x8*)(SA_(cur) + lds_byte<KS>(wr * (MT * 16) + m * 16 + fr, fq * 8));
; #pragma unroll
;       for (int n = 0; n < 4; ++n) Bf0[n] = *(const bf16x8*)(SB_(cur) + lds_byte<KS>(wc * 64 + n * 16 + fr, fq * 8));
; #pragma unroll
;       for (int n = 0; n < 4; ++n) Bf1[n] = *(const bf16x8*)(SB_(cur) + lds_byte<KS>(wc * 64 + n * 16 + fr, 32 + fq * 8));
;       __builtin_amdgcn_s_setprio(1);
; #pragma unroll
;       for (int m = 0; m < MT; ++m) {
; #pragma unroll
;         for (int n = 0; n < 4; ++n) acc[m][n] = __builtin_amdgcn_mfma_f32_16x16x32_bf16(Bf0[n], At[m], acc[m][n], 0, 0, 0);
;         At[m] = *(const bf16x8*)(SA_(cur) + lds_byte<KS>(wr * (MT * 16) + m * 16 + fr, 32 + fq * 8));
;       }
; #pragma unroll
;       for (int m = 0; m < MT; ++m)
; #pragma unroll
;         for (int n = 0; n < 4; ++n) acc[m][n] = __builtin_amdgcn_mfma_f32_16x16x32_bf16(Bf1[n], At[m], acc[m][n], 0, 0, 0);
;       __builtin_amdgcn_s_setprio(0);
;       __builtin_amdgcn_sched_barrier(0);
;     }
;     WAIT_V0();
;     __syncthreads();
;   }
;   {
;     float* eb = (float*)(shm + wid * 16384);
;     const int row0 = brow + wr * (MT * 16), col0 = __builtin_amdgcn_readfirstlane(bcol + wc * 64);
; #pragma unroll
;     for (int hf = 0; hf < MT / 4; ++hf) {
; #pragma unroll
;       for (int mm = 0; mm < 4; ++mm)
; #pragma unroll
;         for (int n = 0; n < 4; ++n) {
;           const int r = mm * 16 + fr, ch = n * 4 + fq;
;           *(f32x4*)(eb + r * 64 + ((ch ^ (r & 15)) << 2)) = acc[hf * 4 + mm][n];
.LBB0_590:
	s_cmpk_eq_i32 s20, 0x380
	s_mov_b32 s22, 0x10000
	s_cbranch_scc1 .LBB0_589
	s_and_b32 s22, s7, 0x10000
	s_xor_b32 s23, s22, 0x10000
	v_add_u32_e32 v94, s23, v80
	v_add_u32_e32 v95, 0x2000, v94
	v_readfirstlane_b32 s23, v94
	v_lshl_add_u64 v[92:93], v[74:75], 0, s[20:21]
	s_mov_b32 m0, s23
	v_readfirstlane_b32 s23, v95
	v_add_u32_e32 v95, 0x8000, v94
	global_load_lds_dwordx4 v[92:93], off
	v_lshl_add_u64 v[92:93], v[72:73], 0, s[20:21]
	s_mov_b32 m0, s23
	v_readfirstlane_b32 s23, v95
	v_add_u32_e32 v95, 0xa000, v94
	global_load_lds_dwordx4 v[92:93], off
	v_lshl_add_u64 v[92:93], v[70:71], 0, s[20:21]
	s_mov_b32 m0, s23
	v_readfirstlane_b32 s23, v95
	v_add_u32_e32 v95, 0xc000, v94
	global_load_lds_dwordx4 v[92:93], off
	v_lshl_add_u64 v[92:93], v[68:69], 0, s[20:21]
	s_mov_b32 m0, s23
	v_readfirstlane_b32 s23, v95
	v_add_u32_e32 v94, 0xe000, v94
	global_load_lds_dwordx4 v[92:93], off
	v_lshl_add_u64 v[92:93], v[66:67], 0, s[20:21]
	s_mov_b32 m0, s23
	v_readfirstlane_b32 s23, v94
	global_load_lds_dwordx4 v[92:93], off
	v_lshl_add_u64 v[92:93], v[64:65], 0, s[20:21]
	s_mov_b32 m0, s23
	s_nop 0
	global_load_lds_dwordx4 v[92:93], off
	s_branch .LBB0_589
.Ltramp_1:
	s_branch .LBB0_343
.Ltramp_2:
	s_branch .LBB0_343
.LBB0_592:
	v_lshrrev_b32_e32 v66, 4, v79
	v_lshlrev_b32_e32 v67, 14, v78
	v_lshl_or_b32 v70, v77, 8, v67
	v_xor_b32_e32 v71, v66, v77
	v_lshl_or_b32 v71, v71, 4, v70
	ds_write_b128 v71, v[40:43]
	v_bitop3_b32 v40, v66, v77, 4 bitop3:0x36
	v_lshl_or_b32 v40, v40, 4, v70
	v_lshl_or_b32 v64, v81, 6, s6
	ds_write_b128 v40, v[28:31]
	v_bitop3_b32 v28, v66, v77, 8 bitop3:0x36
	v_readfirstlane_b32 s7, v64
	v_lshl_or_b32 v28, v28, 4, v70
	ds_write_b128 v28, v[20:23]
	v_add_u32_e32 v64, s7, v83
	v_bitop3_b32 v20, v66, v77, 12 bitop3:0x36
	s_lshl_b32 s7, s30, 8
	v_lshl_or_b32 v20, v20, 4, v70
	s_or_b32 s7, s19, s7
	v_ashrrev_i32_e32 v65, 31, v64
	ds_write_b128 v20, v[16:19]
	ds_write_b128 v71, v[12:15] offset:4096
	ds_write_b128 v40, v[8:11] offset:4096
	ds_write_b128 v28, v[4:7] offset:4096
	ds_write_b128 v20, v[0:3] offset:4096
	ds_write_b128 v71, v[24:27] offset:8192
	ds_write_b128 v40, v[32:35] offset:8192
	ds_write_b128 v28, v[36:39] offset:8192
	ds_write_b128 v20, v[44:47] offset:8192
	ds_write_b128 v71, v[48:51] offset:12288
	ds_write_b128 v40, v[52:55] offset:12288
	ds_write_b128 v28, v[56:59] offset:12288
	ds_write_b128 v20, v[60:63] offset:12288
	v_add3_u32 v2, s7, v66, v82
	s_lshl_b32 s7, s31, 8
	v_lshlrev_b64 v[68:69], 1, v[64:65]
	v_subrev_u32_e32 v2, s7, v2
	v_lshl_add_u64 v[64:65], s[10:11], 0, v[68:69]
	v_lshl_add_u64 v[0:1], s[12:13], 0, v[68:69]
	v_subrev_u32_e32 v2, s44, v2
	v_lshl_or_b32 v3, v66, 8, v67
	s_mov_b32 s7, 0

; DEV void scan_phase(const Params& p, char* smem, const float* __restrict__ nx, const float* __restrict__ ng, u16* __restrict__ nh) {
;     ...
;       if (consumer) {
;         const float* ob = opsb + cur * 10240 + kseg * 4;
;         const float* vb = vbb + cur * 512 + row;
;         float* yb = ybb + cur * 512 + row * 32;
;         float4 r4 = *(const float4*)(ob), w4 = *(const float4*)(ob + 64), k4 = *(const float4*)(ob + 128);
;         float4 a4 = *(const float4*)(ob + 192), b4 = *(const float4*)(ob + 256);
;         float v = vb[0];
; #pragma unroll 1
;         for (int s4 = 0; s4 < 8; ++s4) {
;           float yv[4];
; #pragma unroll
;           for (int u = 0; u < 4; ++u) {
;             const int step = s4 * 4 + u;
;             const float* o = ob + ((step + 1) & 31) * 320;
;             const float4 nr4 = *(const float4*)(o), nw4 = *(const float4*)(o + 64), nk4 = *(const float4*)(o + 128);
;             const float4 na4 = *(const float4*)(o + 192), nb4 = *(const float4*)(o + 256);
;             const float nv = vb[((step + 1) & 31) * 16];
;             __builtin_amdgcn_sched_barrier(0);
;             const f32x2 vv = {v, v};
;             f32x2 sa2 = s01 * f32x2{a4.x, a4.y};
;             sa2 = s23 * f32x2{a4.z, a4.w} + sa2;
;             float sa = sa2.x + sa2.y;
;             f32x2 t01 = s01 * f32x2{w4.x, w4.y};
;             f32x2 t23 = s23 * f32x2{w4.z, w4.w};
;             t01 = vv * f32x2{k4.x, k4.y} + t01;
;             t23 = vv * f32x2{k4.z, k4.w} + t23;
;             sa = reduce16(sa);
;             const f32x2 sav = {sa, sa};
;             s01 = sav * f32x2{b4.x, b4.y} + t01;
;             s23 = sav * f32x2{b4.z, b4.w} + t23;
;             f32x2 y2 = s01 * f32x2{r4.x, r4.y};
;             y2 = s23 * f32x2{r4.z, r4.w} + y2;
;             yv[u] = reduce16(y2.x + y2.y);
;             r4 = nr4; w4 = nw4; k4 = nk4; a4 = na4; b4 = nb4; v = nv;
;           }
;           *(float4*)(yb + s4 * 4) = float4{yv[0], yv[1], yv[2], yv[3]};
;         }
.LBB0_657:
	s_andn2_saveexec_b64 s[72:73], s[90:91]
	s_cbranch_execz .LBB0_644
	v_cndmask_b32_e64 v40, 0, 1, s[92:93]
	s_mov_b32 s41, 0xa000
	v_lshlrev_b32_e32 v41, 11, v40
	v_mul_lo_u32 v40, v40, s41
	s_mul_i32 s41, s40, 0xa000
	v_or_b32_e32 v97, s41, v129
	v_or_b32_e32 v91, v132, v41
	v_or_b32_e32 v93, v133, v40
	v_lshl_add_u32 v134, s40, 11, v128
	ds_read_b128 v[56:59], v97 offset:768
	ds_read_b128 v[52:55], v97 offset:512
	ds_read_b32 v104, v134
	ds_read_b128 v[44:47], v97 offset:256
	ds_read_b128 v[48:51], v97 offset:1024
	ds_read_b128 v[40:43], v97
	v_bfe_u32 v95, v129, 6, 2
	v_lshl_add_u32 v91, v95, 2, v91
	v_add_u32_e32 v91, 0x15000, v91
	v_add_u32_e32 v95, 64, v134
	s_waitcnt lgkmcnt(2)
	v_pk_mul_f32 v[164:165], v[100:101], v[56:57]
	ds_read_b128 v[146:149], v93 offset:768
	v_pk_fma_f32 v[164:165], v[102:103], v[58:59], v[164:165]
	ds_read_b128 v[142:145], v93 offset:512
	v_add_f32_e32 v164, v164, v165
	ds_read_b32 v158, v95
	ds_read_b128 v[136:139], v93 offset:256
	v_add_f32_dpp v164, v164, v164 quad_perm:[1,0,3,2] row_mask:0xf bank_mask:0xf bound_ctrl:1
	v_pk_mul_f32 v[160:161], v[52:53], v[104:105] op_sel_hi:[1,0]
	v_pk_mul_f32 v[162:163], v[54:55], v[104:105] op_sel_hi:[1,0]
	v_add_f32_dpp v164, v164, v164 quad_perm:[2,3,0,1] row_mask:0xf bank_mask:0xf bound_ctrl:1
	v_pk_fma_f32 v[160:161], v[100:101], v[44:45], v[160:161]
	v_pk_fma_f32 v[162:163], v[102:103], v[46:47], v[162:163]
	v_add_f32_dpp v164, v164, v164 row_half_mirror row_mask:0xf bank_mask:0xf bound_ctrl:1
	ds_read_b128 v[150:153], v93 offset:1024
	ds_read_b128 v[154:157], v93
	v_add_f32_dpp v164, v164, v164 row_mirror row_mask:0xf bank_mask:0xf bound_ctrl:1
	s_waitcnt lgkmcnt(6)
	v_pk_fma_f32 v[100:101], v[48:49], v[164:165], v[160:161] op_sel_hi:[1,0,1]
	v_pk_fma_f32 v[102:103], v[50:51], v[164:165], v[162:163] op_sel_hi:[1,0,1]
	v_pk_mul_f32 v[164:165], v[100:101], v[40:41]
	v_pk_fma_f32 v[164:165], v[102:103], v[42:43], v[164:165]
	v_add_f32_e32 v97, v164, v165
	s_waitcnt lgkmcnt(2)
	v_pk_mul_f32 v[164:165], v[100:101], v[146:147]
	ds_read_b128 v[56:59], v93 offset:2048
	v_pk_fma_f32 v[164:165], v[102:103], v[148:149], v[164:165]
	ds_read_b128 v[52:55], v93 offset:1792
	v_add_f32_e32 v164, v164, v165
	ds_read_b32 v104, v95 offset:64
	ds_read_b128 v[44:47], v93 offset:1536
	v_add_f32_dpp v164, v164, v164 quad_perm:[1,0,3,2] row_mask:0xf bank_mask:0xf bound_ctrl:1
	v_pk_mul_f32 v[160:161], v[142:143], v[158:159] op_sel_hi:[1,0]
	v_pk_mul_f32 v[162:163], v[144:145], v[158:159] op_sel_hi:[1,0]
	v_add_f32_dpp v164, v164, v164 quad_perm:[2,3,0,1] row_mask:0xf bank_mask:0xf bound_ctrl:1
	v_pk_fma_f32 v[160:161], v[100:101], v[136:137], v[160:161]
	v_pk_fma_f32 v[162:163], v[102:103], v[138:139], v[162:163]
	v_add_f32_dpp v164, v164, v164 row_half_mirror row_mask:0xf bank_mask:0xf bound_ctrl:1
	ds_read_b128 v[48:51], v93 offset:2304
	ds_read_b128 v[40:43], v93 offset:1280
	v_add_f32_dpp v164, v164, v164 row_mirror row_mask:0xf bank_mask:0xf bound_ctrl:1
	s_waitcnt lgkmcnt(6)
	v_pk_fma_f32 v[100:101], v[150:151], v[164:165], v[160:161] op_sel_hi:[1,0,1]
	v_pk_fma_f32 v[102:103], v[152:153], v[164:165], v[162:163] op_sel_hi:[1,0,1]
	v_pk_mul_f32 v[164:165], v[100:101], v[154:155]
	v_pk_fma_f32 v[164:165], v[102:103], v[156:157], v[164:165]
	v_add_f32_e32 v159, v164, v165
	s_waitcnt lgkmcnt(2)
	v_pk_mul_f32 v[164:165], v[100:101], v[56:57]
	ds_read_b128 v[146:149], v93 offset:3328
	v_pk_fma_f32 v[164:165], v[102:103], v[58:59], v[164:165]
	ds_read_b128 v[142:145], v93 offset:3072
	v_add_f32_dpp v135, v97, v97 row_half_mirror row_mask:0xf bank_mask:0x5 bound_ctrl:1
	v_add_f32_e32 v164, v164, v165
	ds_read_b32 v158, v95 offset:128
	ds_read_b128 v[136:139], v93 offset:2816
	v_add_f32_dpp v164, v164, v164 quad_perm:[1,0,3,2] row_mask:0xf bank_mask:0xf bound_ctrl:1
	v_pk_mul_f32 v[160:161], v[52:53], v[104:105] op_sel_hi:[1,0]
	v_pk_mul_f32 v[162:163], v[54:55], v[104:105] op_sel_hi:[1,0]
	v_add_f32_dpp v164, v164, v164 quad_perm:[2,3,0,1] row_mask:0xf bank_mask:0xf bound_ctrl:1
	v_pk_fma_f32 v[160:161], v[100:101], v[44:45], v[160:161]
	v_pk_fma_f32 v[162:163], v[102:103], v[46:47], v[162:163]
	v_add_f32_dpp v164, v164, v164 row_half_mirror row_mask:0xf bank_mask:0xf bound_ctrl:1
	ds_read_b128 v[150:153], v93 offset:3584
	ds_read_b128 v[154:157], v93 offset:2560
	v_add_f32_dpp v164, v164, v164 row_mirror row_mask:0xf bank_mask:0xf bound_ctrl:1
	s_waitcnt lgkmcnt(6)
	v_add_f32_dpp v135, v159, v159 row_half_mirror row_mask:0xf bank_mask:0xa bound_ctrl:1
	v_pk_fma_f32 v[100:101], v[48:49], v[164:165], v[160:161] op_sel_hi:[1,0,1]
	v_pk_fma_f32 v[102:103], v[50:51], v[164:165], v[162:163] op_sel_hi:[1,0,1]
	v_pk_mul_f32 v[164:165], v[100:101], v[40:41]
	v_pk_fma_f32 v[164:165], v[102:103], v[42:43], v[164:165]
	v_add_f32_e32 v97, v164, v165
	s_waitcnt lgkmcnt(2)
	v_pk_mul_f32 v[164:165], v[100:101], v[146:147]
	ds_read_b128 v[56:59], v93 offset:4608
	v_pk_fma_f32 v[164:165], v[102:103], v[148:149], v[164:165]
	ds_read_b128 v[52:55], v93 offset:4352
	v_add_f32_dpp v134, v97, v97 row_half_mirror row_mask:0xf bank_mask:0x5 bound_ctrl:1
	v_add_f32_e32 v164, v164, v165
	ds_read_b32 v104, v95 offset:192
	ds_read_b128 v[44:47], v93 offset:4096
	v_add_f32_dpp v164, v164, v164 quad_perm:[1,0,3,2] row_mask:0xf bank_mask:0xf bound_ctrl:1
	v_pk_mul_f32 v[160:161], v[142:143], v[158:159] op_sel_hi:[1,0]
	v_pk_mul_f32 v[162:163], v[144:145], v[158:159] op_sel_hi:[1,0]
	v_add_f32_dpp v164, v164, v164 quad_perm:[2,3,0,1] row_mask:0xf bank_mask:0xf bound_ctrl:1
	v_pk_fma_f32 v[160:161], v[100:101], v[136:137], v[160:161]
	v_pk_fma_f32 v[162:163], v[102:103], v[138:139], v[162:163]
	v_add_f32_dpp v164, v164, v164 row_half_mirror row_mask:0xf bank_mask:0xf bound_ctrl:1
	ds_read_b128 v[48:51], v93 offset:4864
	ds_read_b128 v[40:43], v93 offset:3840
	v_add_f32_dpp v164, v164, v164 row_mirror row_mask:0xf bank_mask:0xf bound_ctrl:1
	s_waitcnt lgkmcnt(6)
; DEV void scan_phase(const Params& p, char* smem, const float* __restrict__ nx, const float* __restrict__ ng, u16* __restrict__ nh) {
;     ...
;         for (int s4 = 0; s4 < 8; ++s4) {
;           float yv[4];
; #pragma unroll
;           for (int u = 0; u < 4; ++u) {
;             const int step = s4 * 4 + u;
;             const float* o = ob + ((step + 1) & 31) * 320;
;             const float4 nr4 = *(const float4*)(o), nw4 = *(const float4*)(o + 64), nk4 = *(const float4*)(o + 128);
;             const float4 na4 = *(const float4*)(o + 192), nb4 = *(const float4*)(o + 256);
;             const float nv = vb[((step + 1) & 31) * 16];
;             __builtin_amdgcn_sched_barrier(0);
;             const f32x2 vv = {v, v};
;             f32x2 sa2 = s01 * f32x2{a4.x, a4.y};
;             sa2 = s23 * f32x2{a4.z, a4.w} + sa2;
;             float sa = sa2.x + sa2.y;
;             f32x2 t01 = s01 * f32x2{w4.x, w4.y};
;             f32x2 t23 = s23 * f32x2{w4.z, w4.w};
;             t01 = vv * f32x2{k4.x, k4.y} + t01;
;             t23 = vv * f32x2{k4.z, k4.w} + t23;
;             sa = reduce16(sa);
;             const f32x2 sav = {sa, sa};
;             s01 = sav * f32x2{b4.x, b4.y} + t01;
;             s23 = sav * f32x2{b4.z, b4.w} + t23;
;             f32x2 y2 = s01 * f32x2{r4.x, r4.y};
;             y2 = s23 * f32x2{r4.z, r4.w} + y2;
;             yv[u] = reduce16(y2.x + y2.y);
;             r4 = nr4; w4 = nw4; k4 = nk4; a4 = na4; b4 = nb4; v = nv;
;           }
;           *(float4*)(yb + s4 * 4) = float4{yv[0], yv[1], yv[2], yv[3]};
;         }
	v_pk_fma_f32 v[100:101], v[150:151], v[164:165], v[160:161] op_sel_hi:[1,0,1]
	v_pk_fma_f32 v[102:103], v[152:153], v[164:165], v[162:163] op_sel_hi:[1,0,1]
	v_pk_mul_f32 v[164:165], v[100:101], v[154:155]
	v_pk_fma_f32 v[164:165], v[102:103], v[156:157], v[164:165]
	v_add_f32_e32 v159, v164, v165
	s_nop 1
	v_add_f32_dpp v134, v159, v159 row_half_mirror row_mask:0xf bank_mask:0xa bound_ctrl:1
	s_waitcnt lgkmcnt(2)
	v_pk_mul_f32 v[164:165], v[100:101], v[56:57]
	ds_read_b128 v[146:149], v93 offset:5888
	v_pk_fma_f32 v[164:165], v[102:103], v[58:59], v[164:165]
	ds_read_b128 v[142:145], v93 offset:5632
	v_add_f32_dpp v135, v135, v135 row_ror:8 row_mask:0xf bank_mask:0x3 bound_ctrl:1
	v_add_f32_e32 v164, v164, v165
	ds_read_b32 v158, v95 offset:256
	ds_read_b128 v[136:139], v93 offset:5376
	v_add_f32_dpp v164, v164, v164 quad_perm:[1,0,3,2] row_mask:0xf bank_mask:0xf bound_ctrl:1
	v_pk_mul_f32 v[160:161], v[52:53], v[104:105] op_sel_hi:[1,0]
	v_pk_mul_f32 v[162:163], v[54:55], v[104:105] op_sel_hi:[1,0]
	v_add_f32_dpp v164, v164, v164 quad_perm:[2,3,0,1] row_mask:0xf bank_mask:0xf bound_ctrl:1
	v_pk_fma_f32 v[160:161], v[100:101], v[44:45], v[160:161]
	v_pk_fma_f32 v[162:163], v[102:103], v[46:47], v[162:163]
	v_add_f32_dpp v164, v164, v164 row_half_mirror row_mask:0xf bank_mask:0xf bound_ctrl:1
	ds_read_b128 v[150:153], v93 offset:6144
	ds_read_b128 v[154:157], v93 offset:5120
	v_add_f32_dpp v164, v164, v164 row_mirror row_mask:0xf bank_mask:0xf bound_ctrl:1
	s_waitcnt lgkmcnt(6)
	v_add_f32_dpp v135, v134, v134 row_ror:8 row_mask:0xf bank_mask:0xc bound_ctrl:1
	v_pk_fma_f32 v[100:101], v[48:49], v[164:165], v[160:161] op_sel_hi:[1,0,1]
	v_pk_fma_f32 v[102:103], v[50:51], v[164:165], v[162:163] op_sel_hi:[1,0,1]
	v_add_f32_dpp v135, v135, v135 quad_perm:[1,0,3,2] row_mask:0xf bank_mask:0xf bound_ctrl:1
	v_pk_mul_f32 v[164:165], v[100:101], v[40:41]
	v_pk_fma_f32 v[164:165], v[102:103], v[42:43], v[164:165]
	v_add_f32_dpp v135, v135, v135 quad_perm:[2,3,0,1] row_mask:0xf bank_mask:0xf bound_ctrl:1
	v_add_f32_e32 v97, v164, v165
	s_waitcnt lgkmcnt(2)
	v_pk_mul_f32 v[164:165], v[100:101], v[146:147]
	ds_read_b128 v[56:59], v93 offset:7168
	v_pk_fma_f32 v[164:165], v[102:103], v[148:149], v[164:165]
	ds_read_b128 v[52:55], v93 offset:6912
	ds_write_b32 v91, v135
	v_add_f32_e32 v164, v164, v165
	ds_read_b32 v104, v95 offset:320
	ds_read_b128 v[44:47], v93 offset:6656
	v_add_f32_dpp v164, v164, v164 quad_perm:[1,0,3,2] row_mask:0xf bank_mask:0xf bound_ctrl:1
	v_pk_mul_f32 v[160:161], v[142:143], v[158:159] op_sel_hi:[1,0]
	v_pk_mul_f32 v[162:163], v[144:145], v[158:159] op_sel_hi:[1,0]
	v_add_f32_dpp v164, v164, v164 quad_perm:[2,3,0,1] row_mask:0xf bank_mask:0xf bound_ctrl:1
	v_pk_fma_f32 v[160:161], v[100:101], v[136:137], v[160:161]
	v_pk_fma_f32 v[162:163], v[102:103], v[138:139], v[162:163]
	v_add_f32_dpp v164, v164, v164 row_half_mirror row_mask:0xf bank_mask:0xf bound_ctrl:1
	ds_read_b128 v[48:51], v93 offset:7424
	ds_read_b128 v[40:43], v93 offset:6400
	v_add_f32_dpp v164, v164, v164 row_mirror row_mask:0xf bank_mask:0xf bound_ctrl:1
	s_waitcnt lgkmcnt(6)
	v_pk_fma_f32 v[100:101], v[150:151], v[164:165], v[160:161] op_sel_hi:[1,0,1]
	v_pk_fma_f32 v[102:103], v[152:153], v[164:165], v[162:163] op_sel_hi:[1,0,1]
	v_pk_mul_f32 v[164:165], v[100:101], v[154:155]
	v_pk_fma_f32 v[164:165], v[102:103], v[156:157], v[164:165]
	v_add_f32_e32 v159, v164, v165
	s_waitcnt lgkmcnt(2)
	v_pk_mul_f32 v[164:165], v[100:101], v[56:57]
	ds_read_b128 v[146:149], v93 offset:8448
	v_pk_fma_f32 v[164:165], v[102:103], v[58:59], v[164:165]
	ds_read_b128 v[142:145], v93 offset:8192
	v_add_f32_dpp v0, v97, v97 row_half_mirror row_mask:0xf bank_mask:0x5 bound_ctrl:1
	v_add_f32_e32 v164, v164, v165
	ds_read_b32 v158, v95 offset:384
	ds_read_b128 v[136:139], v93 offset:7936
	v_add_f32_dpp v164, v164, v164 quad_perm:[1,0,3,2] row_mask:0xf bank_mask:0xf bound_ctrl:1
	v_pk_mul_f32 v[160:161], v[52:53], v[104:105] op_sel_hi:[1,0]
	v_pk_mul_f32 v[162:163], v[54:55], v[104:105] op_sel_hi:[1,0]
	v_add_f32_dpp v164, v164, v164 quad_perm:[2,3,0,1] row_mask:0xf bank_mask:0xf bound_ctrl:1
	v_pk_fma_f32 v[160:161], v[100:101], v[44:45], v[160:161]
	v_pk_fma_f32 v[162:163], v[102:103], v[46:47], v[162:163]
	v_add_f32_dpp v164, v164, v164 row_half_mirror row_mask:0xf bank_mask:0xf bound_ctrl:1
	ds_read_b128 v[150:153], v93 offset:8704
	ds_read_b128 v[154:157], v93 offset:7680
	v_add_f32_dpp v164, v164, v164 row_mirror row_mask:0xf bank_mask:0xf bound_ctrl:1
	s_waitcnt lgkmcnt(6)
	v_add_f32_dpp v0, v159, v159 row_half_mirror row_mask:0xf bank_mask:0xa bound_ctrl:1
	v_pk_fma_f32 v[100:101], v[48:49], v[164:165], v[160:161] op_sel_hi:[1,0,1]
	v_pk_fma_f32 v[102:103], v[50:51], v[164:165], v[162:163] op_sel_hi:[1,0,1]
	v_pk_mul_f32 v[164:165], v[100:101], v[40:41]
	v_pk_fma_f32 v[164:165], v[102:103], v[42:43], v[164:165]
	v_add_f32_e32 v97, v164, v165
	s_waitcnt lgkmcnt(2)
	v_pk_mul_f32 v[164:165], v[100:101], v[146:147]
	ds_read_b128 v[56:59], v93 offset:9728
	v_pk_fma_f32 v[164:165], v[102:103], v[148:149], v[164:165]
	ds_read_b128 v[52:55], v93 offset:9472
	v_add_f32_dpp v1, v97, v97 row_half_mirror row_mask:0xf bank_mask:0x5 bound_ctrl:1
	v_add_f32_e32 v164, v164, v165
	ds_read_b32 v104, v95 offset:448
	ds_read_b128 v[44:47], v93 offset:9216
	v_add_f32_dpp v164, v164, v164 quad_perm:[1,0,3,2] row_mask:0xf bank_mask:0xf bound_ctrl:1
	v_pk_mul_f32 v[160:161], v[142:143], v[158:159] op_sel_hi:[1,0]
	v_pk_mul_f32 v[162:163], v[144:145], v[158:159] op_sel_hi:[1,0]
	v_add_f32_dpp v164, v164, v164 quad_perm:[2,3,0,1] row_mask:0xf bank_mask:0xf bound_ctrl:1
	v_pk_fma_f32 v[160:161], v[100:101], v[136:137], v[160:161]
	v_pk_fma_f32 v[162:163], v[102:103], v[138:139], v[162:163]
	v_add_f32_dpp v164, v164, v164 row_half_mirror row_mask:0xf bank_mask:0xf bound_ctrl:1
	ds_read_b128 v[48:51], v93 offset:9984
	ds_read_b128 v[40:43], v93 offset:8960
	v_add_f32_dpp v164, v164, v164 row_mirror row_mask:0xf bank_mask:0xf bound_ctrl:1
	s_waitcnt lgkmcnt(6)
; DEV void scan_phase(const Params& p, char* smem, const float* __restrict__ nx, const float* __restrict__ ng, u16* __restrict__ nh) {
;     ...
;         for (int s4 = 0; s4 < 8; ++s4) {
;           float yv[4];
; #pragma unroll
;           for (int u = 0; u < 4; ++u) {
;             const int step = s4 * 4 + u;
;             const float* o = ob + ((step + 1) & 31) * 320;
;             const float4 nr4 = *(const float4*)(o), nw4 = *(const float4*)(o + 64), nk4 = *(const float4*)(o + 128);
;             const float4 na4 = *(const float4*)(o + 192), nb4 = *(const float4*)(o + 256);
;             const float nv = vb[((step + 1) & 31) * 16];
;             __builtin_amdgcn_sched_barrier(0);
;             const f32x2 vv = {v, v};
;             f32x2 sa2 = s01 * f32x2{a4.x, a4.y};
;             sa2 = s23 * f32x2{a4.z, a4.w} + sa2;
;             float sa = sa2.x + sa2.y;
;             f32x2 t01 = s01 * f32x2{w4.x, w4.y};
;             f32x2 t23 = s23 * f32x2{w4.z, w4.w};
;             t01 = vv * f32x2{k4.x, k4.y} + t01;
;             t23 = vv * f32x2{k4.z, k4.w} + t23;
;             sa = reduce16(sa);
;             const f32x2 sav = {sa, sa};
;             s01 = sav * f32x2{b4.x, b4.y} + t01;
;             s23 = sav * f32x2{b4.z, b4.w} + t23;
;             f32x2 y2 = s01 * f32x2{r4.x, r4.y};
;             y2 = s23 * f32x2{r4.z, r4.w} + y2;
;             yv[u] = reduce16(y2.x + y2.y);
;             r4 = nr4; w4 = nw4; k4 = nk4; a4 = na4; b4 = nb4; v = nv;
;           }
;           *(float4*)(yb + s4 * 4) = float4{yv[0], yv[1], yv[2], yv[3]};
;         }
	v_pk_fma_f32 v[100:101], v[150:151], v[164:165], v[160:161] op_sel_hi:[1,0,1]
	v_pk_fma_f32 v[102:103], v[152:153], v[164:165], v[162:163] op_sel_hi:[1,0,1]
	v_pk_mul_f32 v[164:165], v[100:101], v[154:155]
	v_pk_fma_f32 v[164:165], v[102:103], v[156:157], v[164:165]
	v_add_f32_e32 v159, v164, v165
	s_nop 1
	v_add_f32_dpp v1, v159, v159 row_half_mirror row_mask:0xf bank_mask:0xa bound_ctrl:1
	s_waitcnt lgkmcnt(2)
	v_pk_mul_f32 v[164:165], v[100:101], v[56:57]
	ds_read_b128 v[146:149], v93 offset:11008
	v_pk_fma_f32 v[164:165], v[102:103], v[58:59], v[164:165]
	ds_read_b128 v[142:145], v93 offset:10752
	v_add_f32_dpp v0, v0, v0 row_ror:8 row_mask:0xf bank_mask:0x3 bound_ctrl:1
	v_add_f32_e32 v164, v164, v165
	ds_read_b32 v158, v95 offset:512
	ds_read_b128 v[136:139], v93 offset:10496
	v_add_f32_dpp v164, v164, v164 quad_perm:[1,0,3,2] row_mask:0xf bank_mask:0xf bound_ctrl:1
	v_pk_mul_f32 v[160:161], v[52:53], v[104:105] op_sel_hi:[1,0]
	v_pk_mul_f32 v[162:163], v[54:55], v[104:105] op_sel_hi:[1,0]
	v_add_f32_dpp v164, v164, v164 quad_perm:[2,3,0,1] row_mask:0xf bank_mask:0xf bound_ctrl:1
	v_pk_fma_f32 v[160:161], v[100:101], v[44:45], v[160:161]
	v_pk_fma_f32 v[162:163], v[102:103], v[46:47], v[162:163]
	v_add_f32_dpp v164, v164, v164 row_half_mirror row_mask:0xf bank_mask:0xf bound_ctrl:1
	ds_read_b128 v[150:153], v93 offset:11264
	ds_read_b128 v[154:157], v93 offset:10240
	v_add_f32_dpp v164, v164, v164 row_mirror row_mask:0xf bank_mask:0xf bound_ctrl:1
	s_waitcnt lgkmcnt(6)
	v_add_f32_dpp v0, v1, v1 row_ror:8 row_mask:0xf bank_mask:0xc bound_ctrl:1
	v_pk_fma_f32 v[100:101], v[48:49], v[164:165], v[160:161] op_sel_hi:[1,0,1]
	v_pk_fma_f32 v[102:103], v[50:51], v[164:165], v[162:163] op_sel_hi:[1,0,1]
	v_add_f32_dpp v0, v0, v0 quad_perm:[1,0,3,2] row_mask:0xf bank_mask:0xf bound_ctrl:1
	v_pk_mul_f32 v[164:165], v[100:101], v[40:41]
	v_pk_fma_f32 v[164:165], v[102:103], v[42:43], v[164:165]
	v_add_f32_dpp v0, v0, v0 quad_perm:[2,3,0,1] row_mask:0xf bank_mask:0xf bound_ctrl:1
	v_add_f32_e32 v97, v164, v165
	s_waitcnt lgkmcnt(2)
	v_pk_mul_f32 v[164:165], v[100:101], v[146:147]
	ds_read_b128 v[56:59], v93 offset:12288
	v_pk_fma_f32 v[164:165], v[102:103], v[148:149], v[164:165]
	ds_read_b128 v[52:55], v93 offset:12032
	ds_write_b32 v91, v0 offset:16
	v_add_f32_e32 v164, v164, v165
	ds_read_b32 v104, v95 offset:576
	ds_read_b128 v[44:47], v93 offset:11776
	v_add_f32_dpp v164, v164, v164 quad_perm:[1,0,3,2] row_mask:0xf bank_mask:0xf bound_ctrl:1
	v_pk_mul_f32 v[160:161], v[142:143], v[158:159] op_sel_hi:[1,0]
	v_pk_mul_f32 v[162:163], v[144:145], v[158:159] op_sel_hi:[1,0]
	v_add_f32_dpp v164, v164, v164 quad_perm:[2,3,0,1] row_mask:0xf bank_mask:0xf bound_ctrl:1
	v_pk_fma_f32 v[160:161], v[100:101], v[136:137], v[160:161]
	v_pk_fma_f32 v[162:163], v[102:103], v[138:139], v[162:163]
	v_add_f32_dpp v164, v164, v164 row_half_mirror row_mask:0xf bank_mask:0xf bound_ctrl:1
	ds_read_b128 v[48:51], v93 offset:12544
	ds_read_b128 v[40:43], v93 offset:11520
	v_add_f32_dpp v164, v164, v164 row_mirror row_mask:0xf bank_mask:0xf bound_ctrl:1
	s_waitcnt lgkmcnt(6)
	v_pk_fma_f32 v[100:101], v[150:151], v[164:165], v[160:161] op_sel_hi:[1,0,1]
	v_pk_fma_f32 v[102:103], v[152:153], v[164:165], v[162:163] op_sel_hi:[1,0,1]
	v_pk_mul_f32 v[164:165], v[100:101], v[154:155]
	v_pk_fma_f32 v[164:165], v[102:103], v[156:157], v[164:165]
	v_add_f32_e32 v159, v164, v165
	s_waitcnt lgkmcnt(2)
	v_pk_mul_f32 v[164:165], v[100:101], v[56:57]
	ds_read_b128 v[146:149], v93 offset:13568
	v_pk_fma_f32 v[164:165], v[102:103], v[58:59], v[164:165]
	ds_read_b128 v[142:145], v93 offset:13312
	v_add_f32_dpp v135, v97, v97 row_half_mirror row_mask:0xf bank_mask:0x5 bound_ctrl:1
	v_add_f32_e32 v164, v164, v165
	ds_read_b32 v158, v95 offset:640
	ds_read_b128 v[136:139], v93 offset:13056
	v_add_f32_dpp v164, v164, v164 quad_perm:[1,0,3,2] row_mask:0xf bank_mask:0xf bound_ctrl:1
	v_pk_mul_f32 v[160:161], v[52:53], v[104:105] op_sel_hi:[1,0]
	v_pk_mul_f32 v[162:163], v[54:55], v[104:105] op_sel_hi:[1,0]
	v_add_f32_dpp v164, v164, v164 quad_perm:[2,3,0,1] row_mask:0xf bank_mask:0xf bound_ctrl:1
	v_pk_fma_f32 v[160:161], v[100:101], v[44:45], v[160:161]
	v_pk_fma_f32 v[162:163], v[102:103], v[46:47], v[162:163]
	v_add_f32_dpp v164, v164, v164 row_half_mirror row_mask:0xf bank_mask:0xf bound_ctrl:1
	ds_read_b128 v[150:153], v93 offset:13824
	ds_read_b128 v[154:157], v93 offset:12800
	v_add_f32_dpp v164, v164, v164 row_mirror row_mask:0xf bank_mask:0xf bound_ctrl:1
	s_waitcnt lgkmcnt(6)
	v_add_f32_dpp v135, v159, v159 row_half_mirror row_mask:0xf bank_mask:0xa bound_ctrl:1
	v_pk_fma_f32 v[100:101], v[48:49], v[164:165], v[160:161] op_sel_hi:[1,0,1]
	v_pk_fma_f32 v[102:103], v[50:51], v[164:165], v[162:163] op_sel_hi:[1,0,1]
	v_pk_mul_f32 v[164:165], v[100:101], v[40:41]
	v_pk_fma_f32 v[164:165], v[102:103], v[42:43], v[164:165]
	v_add_f32_e32 v97, v164, v165
	s_waitcnt lgkmcnt(2)
	v_pk_mul_f32 v[164:165], v[100:101], v[146:147]
	ds_read_b128 v[56:59], v93 offset:14848
	v_pk_fma_f32 v[164:165], v[102:103], v[148:149], v[164:165]
	ds_read_b128 v[52:55], v93 offset:14592
	v_add_f32_dpp v134, v97, v97 row_half_mirror row_mask:0xf bank_mask:0x5 bound_ctrl:1
	v_add_f32_e32 v164, v164, v165
	ds_read_b32 v104, v95 offset:704
	ds_read_b128 v[44:47], v93 offset:14336
	v_add_f32_dpp v164, v164, v164 quad_perm:[1,0,3,2] row_mask:0xf bank_mask:0xf bound_ctrl:1
	v_pk_mul_f32 v[160:161], v[142:143], v[158:159] op_sel_hi:[1,0]
	v_pk_mul_f32 v[162:163], v[144:145], v[158:159] op_sel_hi:[1,0]
	v_add_f32_dpp v164, v164, v164 quad_perm:[2,3,0,1] row_mask:0xf bank_mask:0xf bound_ctrl:1
	v_pk_fma_f32 v[160:161], v[100:101], v[136:137], v[160:161]
	v_pk_fma_f32 v[162:163], v[102:103], v[138:139], v[162:163]
	v_add_f32_dpp v164, v164, v164 row_half_mirror row_mask:0xf bank_mask:0xf bound_ctrl:1
	ds_read_b128 v[48:51], v93 offset:15104
	ds_read_b128 v[40:43], v93 offset:14080
	v_add_f32_dpp v164, v164, v164 row_mirror row_mask:0xf bank_mask:0xf bound_ctrl:1
	s_waitcnt lgkmcnt(6)
; DEV void scan_phase(const Params& p, char* smem, const float* __restrict__ nx, const float* __restrict__ ng, u16* __restrict__ nh) {
;     ...
;         for (int s4 = 0; s4 < 8; ++s4) {
;           float yv[4];
; #pragma unroll
;           for (int u = 0; u < 4; ++u) {
;             const int step = s4 * 4 + u;
;             const float* o = ob + ((step + 1) & 31) * 320;
;             const float4 nr4 = *(const float4*)(o), nw4 = *(const float4*)(o + 64), nk4 = *(const float4*)(o + 128);
;             const float4 na4 = *(const float4*)(o + 192), nb4 = *(const float4*)(o + 256);
;             const float nv = vb[((step + 1) & 31) * 16];
;             __builtin_amdgcn_sched_barrier(0);
;             const f32x2 vv = {v, v};
;             f32x2 sa2 = s01 * f32x2{a4.x, a4.y};
;             sa2 = s23 * f32x2{a4.z, a4.w} + sa2;
;             float sa = sa2.x + sa2.y;
;             f32x2 t01 = s01 * f32x2{w4.x, w4.y};
;             f32x2 t23 = s23 * f32x2{w4.z, w4.w};
;             t01 = vv * f32x2{k4.x, k4.y} + t01;
;             t23 = vv * f32x2{k4.z, k4.w} + t23;
;             sa = reduce16(sa);
;             const f32x2 sav = {sa, sa};
;             s01 = sav * f32x2{b4.x, b4.y} + t01;
;             s23 = sav * f32x2{b4.z, b4.w} + t23;
;             f32x2 y2 = s01 * f32x2{r4.x, r4.y};
;             y2 = s23 * f32x2{r4.z, r4.w} + y2;
;             yv[u] = reduce16(y2.x + y2.y);
;             r4 = nr4; w4 = nw4; k4 = nk4; a4 = na4; b4 = nb4; v = nv;
;           }
;           *(float4*)(yb + s4 * 4) = float4{yv[0], yv[1], yv[2], yv[3]};
;         }
	v_pk_fma_f32 v[100:101], v[150:151], v[164:165], v[160:161] op_sel_hi:[1,0,1]
	v_pk_fma_f32 v[102:103], v[152:153], v[164:165], v[162:163] op_sel_hi:[1,0,1]
	v_pk_mul_f32 v[164:165], v[100:101], v[154:155]
	v_pk_fma_f32 v[164:165], v[102:103], v[156:157], v[164:165]
	v_add_f32_e32 v159, v164, v165
	s_nop 1
	v_add_f32_dpp v134, v159, v159 row_half_mirror row_mask:0xf bank_mask:0xa bound_ctrl:1
	s_waitcnt lgkmcnt(2)
	v_pk_mul_f32 v[164:165], v[100:101], v[56:57]
	ds_read_b128 v[146:149], v93 offset:16128
	v_pk_fma_f32 v[164:165], v[102:103], v[58:59], v[164:165]
	ds_read_b128 v[142:145], v93 offset:15872
	v_add_f32_dpp v135, v135, v135 row_ror:8 row_mask:0xf bank_mask:0x3 bound_ctrl:1
	v_add_f32_e32 v164, v164, v165
	ds_read_b32 v158, v95 offset:768
	ds_read_b128 v[136:139], v93 offset:15616
	v_add_f32_dpp v164, v164, v164 quad_perm:[1,0,3,2] row_mask:0xf bank_mask:0xf bound_ctrl:1
	v_pk_mul_f32 v[160:161], v[52:53], v[104:105] op_sel_hi:[1,0]
	v_pk_mul_f32 v[162:163], v[54:55], v[104:105] op_sel_hi:[1,0]
	v_add_f32_dpp v164, v164, v164 quad_perm:[2,3,0,1] row_mask:0xf bank_mask:0xf bound_ctrl:1
	v_pk_fma_f32 v[160:161], v[100:101], v[44:45], v[160:161]
	v_pk_fma_f32 v[162:163], v[102:103], v[46:47], v[162:163]
	v_add_f32_dpp v164, v164, v164 row_half_mirror row_mask:0xf bank_mask:0xf bound_ctrl:1
	ds_read_b128 v[150:153], v93 offset:16384
	ds_read_b128 v[154:157], v93 offset:15360
	v_add_f32_dpp v164, v164, v164 row_mirror row_mask:0xf bank_mask:0xf bound_ctrl:1
	s_waitcnt lgkmcnt(6)
	v_add_f32_dpp v135, v134, v134 row_ror:8 row_mask:0xf bank_mask:0xc bound_ctrl:1
	v_pk_fma_f32 v[100:101], v[48:49], v[164:165], v[160:161] op_sel_hi:[1,0,1]
	v_pk_fma_f32 v[102:103], v[50:51], v[164:165], v[162:163] op_sel_hi:[1,0,1]
	v_add_f32_dpp v135, v135, v135 quad_perm:[1,0,3,2] row_mask:0xf bank_mask:0xf bound_ctrl:1
	v_pk_mul_f32 v[164:165], v[100:101], v[40:41]
	v_pk_fma_f32 v[164:165], v[102:103], v[42:43], v[164:165]
	v_add_f32_dpp v135, v135, v135 quad_perm:[2,3,0,1] row_mask:0xf bank_mask:0xf bound_ctrl:1
	v_add_f32_e32 v97, v164, v165
	s_waitcnt lgkmcnt(2)
	v_pk_mul_f32 v[164:165], v[100:101], v[146:147]
	ds_read_b128 v[56:59], v93 offset:17408
	v_pk_fma_f32 v[164:165], v[102:103], v[148:149], v[164:165]
	ds_read_b128 v[52:55], v93 offset:17152
	ds_write_b32 v91, v135 offset:32
	v_add_f32_e32 v164, v164, v165
	ds_read_b32 v104, v95 offset:832
	ds_read_b128 v[44:47], v93 offset:16896
	v_add_f32_dpp v164, v164, v164 quad_perm:[1,0,3,2] row_mask:0xf bank_mask:0xf bound_ctrl:1
	v_pk_mul_f32 v[160:161], v[142:143], v[158:159] op_sel_hi:[1,0]
	v_pk_mul_f32 v[162:163], v[144:145], v[158:159] op_sel_hi:[1,0]
	v_add_f32_dpp v164, v164, v164 quad_perm:[2,3,0,1] row_mask:0xf bank_mask:0xf bound_ctrl:1
	v_pk_fma_f32 v[160:161], v[100:101], v[136:137], v[160:161]
	v_pk_fma_f32 v[162:163], v[102:103], v[138:139], v[162:163]
	v_add_f32_dpp v164, v164, v164 row_half_mirror row_mask:0xf bank_mask:0xf bound_ctrl:1
	ds_read_b128 v[48:51], v93 offset:17664
	ds_read_b128 v[40:43], v93 offset:16640
	v_add_f32_dpp v164, v164, v164 row_mirror row_mask:0xf bank_mask:0xf bound_ctrl:1
	s_waitcnt lgkmcnt(6)
	v_pk_fma_f32 v[100:101], v[150:151], v[164:165], v[160:161] op_sel_hi:[1,0,1]
	v_pk_fma_f32 v[102:103], v[152:153], v[164:165], v[162:163] op_sel_hi:[1,0,1]
	v_pk_mul_f32 v[164:165], v[100:101], v[154:155]
	v_pk_fma_f32 v[164:165], v[102:103], v[156:157], v[164:165]
	v_add_f32_e32 v159, v164, v165
	s_waitcnt lgkmcnt(2)
	v_pk_mul_f32 v[164:165], v[100:101], v[56:57]
	ds_read_b128 v[146:149], v93 offset:18688
	v_pk_fma_f32 v[164:165], v[102:103], v[58:59], v[164:165]
	ds_read_b128 v[142:145], v93 offset:18432
	v_add_f32_dpp v0, v97, v97 row_half_mirror row_mask:0xf bank_mask:0x5 bound_ctrl:1
	v_add_f32_e32 v164, v164, v165
	ds_read_b32 v158, v95 offset:896
	ds_read_b128 v[136:139], v93 offset:18176
	v_add_f32_dpp v164, v164, v164 quad_perm:[1,0,3,2] row_mask:0xf bank_mask:0xf bound_ctrl:1
	v_pk_mul_f32 v[160:161], v[52:53], v[104:105] op_sel_hi:[1,0]
	v_pk_mul_f32 v[162:163], v[54:55], v[104:105] op_sel_hi:[1,0]
	v_add_f32_dpp v164, v164, v164 quad_perm:[2,3,0,1] row_mask:0xf bank_mask:0xf bound_ctrl:1
	v_pk_fma_f32 v[160:161], v[100:101], v[44:45], v[160:161]
	v_pk_fma_f32 v[162:163], v[102:103], v[46:47], v[162:163]
	v_add_f32_dpp v164, v164, v164 row_half_mirror row_mask:0xf bank_mask:0xf bound_ctrl:1
	ds_read_b128 v[150:153], v93 offset:18944
	ds_read_b128 v[154:157], v93 offset:17920
	v_add_f32_dpp v164, v164, v164 row_mirror row_mask:0xf bank_mask:0xf bound_ctrl:1
	s_waitcnt lgkmcnt(6)
	v_add_f32_dpp v0, v159, v159 row_half_mirror row_mask:0xf bank_mask:0xa bound_ctrl:1
	v_pk_fma_f32 v[100:101], v[48:49], v[164:165], v[160:161] op_sel_hi:[1,0,1]
	v_pk_fma_f32 v[102:103], v[50:51], v[164:165], v[162:163] op_sel_hi:[1,0,1]
	v_pk_mul_f32 v[164:165], v[100:101], v[40:41]
	v_pk_fma_f32 v[164:165], v[102:103], v[42:43], v[164:165]
	v_add_f32_e32 v97, v164, v165
	s_waitcnt lgkmcnt(2)
	v_pk_mul_f32 v[164:165], v[100:101], v[146:147]
	ds_read_b128 v[56:59], v93 offset:19968
	v_pk_fma_f32 v[164:165], v[102:103], v[148:149], v[164:165]
	ds_read_b128 v[52:55], v93 offset:19712
	v_add_f32_dpp v1, v97, v97 row_half_mirror row_mask:0xf bank_mask:0x5 bound_ctrl:1
	v_add_f32_e32 v164, v164, v165
	ds_read_b32 v104, v95 offset:960
	ds_read_b128 v[44:47], v93 offset:19456
	v_add_f32_dpp v164, v164, v164 quad_perm:[1,0,3,2] row_mask:0xf bank_mask:0xf bound_ctrl:1
	v_pk_mul_f32 v[160:161], v[142:143], v[158:159] op_sel_hi:[1,0]
	v_pk_mul_f32 v[162:163], v[144:145], v[158:159] op_sel_hi:[1,0]
	v_add_f32_dpp v164, v164, v164 quad_perm:[2,3,0,1] row_mask:0xf bank_mask:0xf bound_ctrl:1
	v_pk_fma_f32 v[160:161], v[100:101], v[136:137], v[160:161]
	v_pk_fma_f32 v[162:163], v[102:103], v[138:139], v[162:163]
	v_add_f32_dpp v164, v164, v164 row_half_mirror row_mask:0xf bank_mask:0xf bound_ctrl:1
	ds_read_b128 v[48:51], v93 offset:20224
	ds_read_b128 v[40:43], v93 offset:19200
	v_add_f32_dpp v164, v164, v164 row_mirror row_mask:0xf bank_mask:0xf bound_ctrl:1
	s_waitcnt lgkmcnt(6)
; DEV void scan_phase(const Params& p, char* smem, const float* __restrict__ nx, const float* __restrict__ ng, u16* __restrict__ nh) {
;     ...
;         for (int s4 = 0; s4 < 8; ++s4) {
;           float yv[4];
; #pragma unroll
;           for (int u = 0; u < 4; ++u) {
;             const int step = s4 * 4 + u;
;             const float* o = ob + ((step + 1) & 31) * 320;
;             const float4 nr4 = *(const float4*)(o), nw4 = *(const float4*)(o + 64), nk4 = *(const float4*)(o + 128);
;             const float4 na4 = *(const float4*)(o + 192), nb4 = *(const float4*)(o + 256);
;             const float nv = vb[((step + 1) & 31) * 16];
;             __builtin_amdgcn_sched_barrier(0);
;             const f32x2 vv = {v, v};
;             f32x2 sa2 = s01 * f32x2{a4.x, a4.y};
;             sa2 = s23 * f32x2{a4.z, a4.w} + sa2;
;             float sa = sa2.x + sa2.y;
;             f32x2 t01 = s01 * f32x2{w4.x, w4.y};
;             f32x2 t23 = s23 * f32x2{w4.z, w4.w};
;             t01 = vv * f32x2{k4.x, k4.y} + t01;
;             t23 = vv * f32x2{k4.z, k4.w} + t23;
;             sa = reduce16(sa);
;             const f32x2 sav = {sa, sa};
;             s01 = sav * f32x2{b4.x, b4.y} + t01;
;             s23 = sav * f32x2{b4.z, b4.w} + t23;
;             f32x2 y2 = s01 * f32x2{r4.x, r4.y};
;             y2 = s23 * f32x2{r4.z, r4.w} + y2;
;             yv[u] = reduce16(y2.x + y2.y);
;             r4 = nr4; w4 = nw4; k4 = nk4; a4 = na4; b4 = nb4; v = nv;
;           }
;           *(float4*)(yb + s4 * 4) = float4{yv[0], yv[1], yv[2], yv[3]};
;         }
	v_pk_fma_f32 v[100:101], v[150:151], v[164:165], v[160:161] op_sel_hi:[1,0,1]
	v_pk_fma_f32 v[102:103], v[152:153], v[164:165], v[162:163] op_sel_hi:[1,0,1]
	v_pk_mul_f32 v[164:165], v[100:101], v[154:155]
	v_pk_fma_f32 v[164:165], v[102:103], v[156:157], v[164:165]
	v_add_f32_e32 v159, v164, v165
	s_nop 1
	v_add_f32_dpp v1, v159, v159 row_half_mirror row_mask:0xf bank_mask:0xa bound_ctrl:1
	s_waitcnt lgkmcnt(2)
	v_pk_mul_f32 v[164:165], v[100:101], v[56:57]
	ds_read_b128 v[146:149], v93 offset:21248
	v_pk_fma_f32 v[164:165], v[102:103], v[58:59], v[164:165]
	ds_read_b128 v[142:145], v93 offset:20992
	v_add_f32_dpp v0, v0, v0 row_ror:8 row_mask:0xf bank_mask:0x3 bound_ctrl:1
	v_add_f32_e32 v164, v164, v165
	ds_read_b32 v158, v95 offset:1024
	ds_read_b128 v[136:139], v93 offset:20736
	v_add_f32_dpp v164, v164, v164 quad_perm:[1,0,3,2] row_mask:0xf bank_mask:0xf bound_ctrl:1
	v_pk_mul_f32 v[160:161], v[52:53], v[104:105] op_sel_hi:[1,0]
	v_pk_mul_f32 v[162:163], v[54:55], v[104:105] op_sel_hi:[1,0]
	v_add_f32_dpp v164, v164, v164 quad_perm:[2,3,0,1] row_mask:0xf bank_mask:0xf bound_ctrl:1
	v_pk_fma_f32 v[160:161], v[100:101], v[44:45], v[160:161]
	v_pk_fma_f32 v[162:163], v[102:103], v[46:47], v[162:163]
	v_add_f32_dpp v164, v164, v164 row_half_mirror row_mask:0xf bank_mask:0xf bound_ctrl:1
	ds_read_b128 v[150:153], v93 offset:21504
	ds_read_b128 v[154:157], v93 offset:20480
	v_add_f32_dpp v164, v164, v164 row_mirror row_mask:0xf bank_mask:0xf bound_ctrl:1
	s_waitcnt lgkmcnt(6)
	v_add_f32_dpp v0, v1, v1 row_ror:8 row_mask:0xf bank_mask:0xc bound_ctrl:1
	v_pk_fma_f32 v[100:101], v[48:49], v[164:165], v[160:161] op_sel_hi:[1,0,1]
	v_pk_fma_f32 v[102:103], v[50:51], v[164:165], v[162:163] op_sel_hi:[1,0,1]
	v_add_f32_dpp v0, v0, v0 quad_perm:[1,0,3,2] row_mask:0xf bank_mask:0xf bound_ctrl:1
	v_pk_mul_f32 v[164:165], v[100:101], v[40:41]
	v_pk_fma_f32 v[164:165], v[102:103], v[42:43], v[164:165]
	v_add_f32_dpp v0, v0, v0 quad_perm:[2,3,0,1] row_mask:0xf bank_mask:0xf bound_ctrl:1
	v_add_f32_e32 v97, v164, v165
	s_waitcnt lgkmcnt(2)
	v_pk_mul_f32 v[164:165], v[100:101], v[146:147]
	ds_read_b128 v[56:59], v93 offset:22528
	v_pk_fma_f32 v[164:165], v[102:103], v[148:149], v[164:165]
	ds_read_b128 v[52:55], v93 offset:22272
	ds_write_b32 v91, v0 offset:48
	v_add_f32_e32 v164, v164, v165
	ds_read_b32 v104, v95 offset:1088
	ds_read_b128 v[44:47], v93 offset:22016
	v_add_f32_dpp v164, v164, v164 quad_perm:[1,0,3,2] row_mask:0xf bank_mask:0xf bound_ctrl:1
	v_pk_mul_f32 v[160:161], v[142:143], v[158:159] op_sel_hi:[1,0]
	v_pk_mul_f32 v[162:163], v[144:145], v[158:159] op_sel_hi:[1,0]
	v_add_f32_dpp v164, v164, v164 quad_perm:[2,3,0,1] row_mask:0xf bank_mask:0xf bound_ctrl:1
	v_pk_fma_f32 v[160:161], v[100:101], v[136:137], v[160:161]
	v_pk_fma_f32 v[162:163], v[102:103], v[138:139], v[162:163]
	v_add_f32_dpp v164, v164, v164 row_half_mirror row_mask:0xf bank_mask:0xf bound_ctrl:1
	ds_read_b128 v[48:51], v93 offset:22784
	ds_read_b128 v[40:43], v93 offset:21760
	v_add_f32_dpp v164, v164, v164 row_mirror row_mask:0xf bank_mask:0xf bound_ctrl:1
	s_waitcnt lgkmcnt(6)
	v_pk_fma_f32 v[100:101], v[150:151], v[164:165], v[160:161] op_sel_hi:[1,0,1]
	v_pk_fma_f32 v[102:103], v[152:153], v[164:165], v[162:163] op_sel_hi:[1,0,1]
	v_pk_mul_f32 v[164:165], v[100:101], v[154:155]
	v_pk_fma_f32 v[164:165], v[102:103], v[156:157], v[164:165]
	v_add_f32_e32 v159, v164, v165
	s_waitcnt lgkmcnt(2)
	v_pk_mul_f32 v[164:165], v[100:101], v[56:57]
	ds_read_b128 v[146:149], v93 offset:23808
	v_pk_fma_f32 v[164:165], v[102:103], v[58:59], v[164:165]
	ds_read_b128 v[142:145], v93 offset:23552
	v_add_f32_dpp v135, v97, v97 row_half_mirror row_mask:0xf bank_mask:0x5 bound_ctrl:1
	v_add_f32_e32 v164, v164, v165
	ds_read_b32 v158, v95 offset:1152
	ds_read_b128 v[136:139], v93 offset:23296
	v_add_f32_dpp v164, v164, v164 quad_perm:[1,0,3,2] row_mask:0xf bank_mask:0xf bound_ctrl:1
	v_pk_mul_f32 v[160:161], v[52:53], v[104:105] op_sel_hi:[1,0]
	v_pk_mul_f32 v[162:163], v[54:55], v[104:105] op_sel_hi:[1,0]
	v_add_f32_dpp v164, v164, v164 quad_perm:[2,3,0,1] row_mask:0xf bank_mask:0xf bound_ctrl:1
	v_pk_fma_f32 v[160:161], v[100:101], v[44:45], v[160:161]
	v_pk_fma_f32 v[162:163], v[102:103], v[46:47], v[162:163]
	v_add_f32_dpp v164, v164, v164 row_half_mirror row_mask:0xf bank_mask:0xf bound_ctrl:1
	ds_read_b128 v[150:153], v93 offset:24064
	ds_read_b128 v[154:157], v93 offset:23040
	v_add_f32_dpp v164, v164, v164 row_mirror row_mask:0xf bank_mask:0xf bound_ctrl:1
	s_waitcnt lgkmcnt(6)
	v_add_f32_dpp v135, v159, v159 row_half_mirror row_mask:0xf bank_mask:0xa bound_ctrl:1
	v_pk_fma_f32 v[100:101], v[48:49], v[164:165], v[160:161] op_sel_hi:[1,0,1]
	v_pk_fma_f32 v[102:103], v[50:51], v[164:165], v[162:163] op_sel_hi:[1,0,1]
	v_pk_mul_f32 v[164:165], v[100:101], v[40:41]
	v_pk_fma_f32 v[164:165], v[102:103], v[42:43], v[164:165]
	v_add_f32_e32 v97, v164, v165
	s_waitcnt lgkmcnt(2)
	v_pk_mul_f32 v[164:165], v[100:101], v[146:147]
	ds_read_b128 v[56:59], v93 offset:25088
	v_pk_fma_f32 v[164:165], v[102:103], v[148:149], v[164:165]
	ds_read_b128 v[52:55], v93 offset:24832
	v_add_f32_dpp v134, v97, v97 row_half_mirror row_mask:0xf bank_mask:0x5 bound_ctrl:1
	v_add_f32_e32 v164, v164, v165
	ds_read_b32 v104, v95 offset:1216
	ds_read_b128 v[44:47], v93 offset:24576
	v_add_f32_dpp v164, v164, v164 quad_perm:[1,0,3,2] row_mask:0xf bank_mask:0xf bound_ctrl:1
	v_pk_mul_f32 v[160:161], v[142:143], v[158:159] op_sel_hi:[1,0]
	v_pk_mul_f32 v[162:163], v[144:145], v[158:159] op_sel_hi:[1,0]
	v_add_f32_dpp v164, v164, v164 quad_perm:[2,3,0,1] row_mask:0xf bank_mask:0xf bound_ctrl:1
	v_pk_fma_f32 v[160:161], v[100:101], v[136:137], v[160:161]
	v_pk_fma_f32 v[162:163], v[102:103], v[138:139], v[162:163]
	v_add_f32_dpp v164, v164, v164 row_half_mirror row_mask:0xf bank_mask:0xf bound_ctrl:1
	ds_read_b128 v[48:51], v93 offset:25344
	ds_read_b128 v[40:43], v93 offset:24320
	v_add_f32_dpp v164, v164, v164 row_mirror row_mask:0xf bank_mask:0xf bound_ctrl:1
	s_waitcnt lgkmcnt(6)
; DEV void scan_phase(const Params& p, char* smem, const float* __restrict__ nx, const float* __restrict__ ng, u16* __restrict__ nh) {
;     ...
;         for (int s4 = 0; s4 < 8; ++s4) {
;           float yv[4];
; #pragma unroll
;           for (int u = 0; u < 4; ++u) {
;             const int step = s4 * 4 + u;
;             const float* o = ob + ((step + 1) & 31) * 320;
;             const float4 nr4 = *(const float4*)(o), nw4 = *(const float4*)(o + 64), nk4 = *(const float4*)(o + 128);
;             const float4 na4 = *(const float4*)(o + 192), nb4 = *(const float4*)(o + 256);
;             const float nv = vb[((step + 1) & 31) * 16];
;             __builtin_amdgcn_sched_barrier(0);
;             const f32x2 vv = {v, v};
;             f32x2 sa2 = s01 * f32x2{a4.x, a4.y};
;             sa2 = s23 * f32x2{a4.z, a4.w} + sa2;
;             float sa = sa2.x + sa2.y;
;             f32x2 t01 = s01 * f32x2{w4.x, w4.y};
;             f32x2 t23 = s23 * f32x2{w4.z, w4.w};
;             t01 = vv * f32x2{k4.x, k4.y} + t01;
;             t23 = vv * f32x2{k4.z, k4.w} + t23;
;             sa = reduce16(sa);
;             const f32x2 sav = {sa, sa};
;             s01 = sav * f32x2{b4.x, b4.y} + t01;
;             s23 = sav * f32x2{b4.z, b4.w} + t23;
;             f32x2 y2 = s01 * f32x2{r4.x, r4.y};
;             y2 = s23 * f32x2{r4.z, r4.w} + y2;
;             yv[u] = reduce16(y2.x + y2.y);
;             r4 = nr4; w4 = nw4; k4 = nk4; a4 = na4; b4 = nb4; v = nv;
;           }
;           *(float4*)(yb + s4 * 4) = float4{yv[0], yv[1], yv[2], yv[3]};
;         }
	v_pk_fma_f32 v[100:101], v[150:151], v[164:165], v[160:161] op_sel_hi:[1,0,1]
	v_pk_fma_f32 v[102:103], v[152:153], v[164:165], v[162:163] op_sel_hi:[1,0,1]
	v_pk_mul_f32 v[164:165], v[100:101], v[154:155]
	v_pk_fma_f32 v[164:165], v[102:103], v[156:157], v[164:165]
	v_add_f32_e32 v159, v164, v165
	s_nop 1
	v_add_f32_dpp v134, v159, v159 row_half_mirror row_mask:0xf bank_mask:0xa bound_ctrl:1
	s_waitcnt lgkmcnt(2)
	v_pk_mul_f32 v[164:165], v[100:101], v[56:57]
	ds_read_b128 v[146:149], v93 offset:26368
	v_pk_fma_f32 v[164:165], v[102:103], v[58:59], v[164:165]
	ds_read_b128 v[142:145], v93 offset:26112
	v_add_f32_dpp v135, v135, v135 row_ror:8 row_mask:0xf bank_mask:0x3 bound_ctrl:1
	v_add_f32_e32 v164, v164, v165
	ds_read_b32 v158, v95 offset:1280
	ds_read_b128 v[136:139], v93 offset:25856
	v_add_f32_dpp v164, v164, v164 quad_perm:[1,0,3,2] row_mask:0xf bank_mask:0xf bound_ctrl:1
	v_pk_mul_f32 v[160:161], v[52:53], v[104:105] op_sel_hi:[1,0]
	v_pk_mul_f32 v[162:163], v[54:55], v[104:105] op_sel_hi:[1,0]
	v_add_f32_dpp v164, v164, v164 quad_perm:[2,3,0,1] row_mask:0xf bank_mask:0xf bound_ctrl:1
	v_pk_fma_f32 v[160:161], v[100:101], v[44:45], v[160:161]
	v_pk_fma_f32 v[162:163], v[102:103], v[46:47], v[162:163]
	v_add_f32_dpp v164, v164, v164 row_half_mirror row_mask:0xf bank_mask:0xf bound_ctrl:1
	ds_read_b128 v[150:153], v93 offset:26624
	ds_read_b128 v[154:157], v93 offset:25600
	v_add_f32_dpp v164, v164, v164 row_mirror row_mask:0xf bank_mask:0xf bound_ctrl:1
	s_waitcnt lgkmcnt(6)
	v_add_f32_dpp v135, v134, v134 row_ror:8 row_mask:0xf bank_mask:0xc bound_ctrl:1
	v_pk_fma_f32 v[100:101], v[48:49], v[164:165], v[160:161] op_sel_hi:[1,0,1]
	v_pk_fma_f32 v[102:103], v[50:51], v[164:165], v[162:163] op_sel_hi:[1,0,1]
	v_add_f32_dpp v135, v135, v135 quad_perm:[1,0,3,2] row_mask:0xf bank_mask:0xf bound_ctrl:1
	v_pk_mul_f32 v[164:165], v[100:101], v[40:41]
	v_pk_fma_f32 v[164:165], v[102:103], v[42:43], v[164:165]
	v_add_f32_dpp v135, v135, v135 quad_perm:[2,3,0,1] row_mask:0xf bank_mask:0xf bound_ctrl:1
	v_add_f32_e32 v97, v164, v165
	s_waitcnt lgkmcnt(2)
	v_pk_mul_f32 v[164:165], v[100:101], v[146:147]
	ds_read_b128 v[56:59], v93 offset:27648
	v_pk_fma_f32 v[164:165], v[102:103], v[148:149], v[164:165]
	ds_read_b128 v[52:55], v93 offset:27392
	ds_write_b32 v91, v135 offset:64
	v_add_f32_e32 v164, v164, v165
	ds_read_b32 v104, v95 offset:1344
	ds_read_b128 v[44:47], v93 offset:27136
	v_add_f32_dpp v164, v164, v164 quad_perm:[1,0,3,2] row_mask:0xf bank_mask:0xf bound_ctrl:1
	v_pk_mul_f32 v[160:161], v[142:143], v[158:159] op_sel_hi:[1,0]
	v_pk_mul_f32 v[162:163], v[144:145], v[158:159] op_sel_hi:[1,0]
	v_add_f32_dpp v164, v164, v164 quad_perm:[2,3,0,1] row_mask:0xf bank_mask:0xf bound_ctrl:1
	v_pk_fma_f32 v[160:161], v[100:101], v[136:137], v[160:161]
	v_pk_fma_f32 v[162:163], v[102:103], v[138:139], v[162:163]
	v_add_f32_dpp v164, v164, v164 row_half_mirror row_mask:0xf bank_mask:0xf bound_ctrl:1
	ds_read_b128 v[48:51], v93 offset:27904
	ds_read_b128 v[40:43], v93 offset:26880
	v_add_f32_dpp v164, v164, v164 row_mirror row_mask:0xf bank_mask:0xf bound_ctrl:1
	s_waitcnt lgkmcnt(6)
	v_pk_fma_f32 v[100:101], v[150:151], v[164:165], v[160:161] op_sel_hi:[1,0,1]
	v_pk_fma_f32 v[102:103], v[152:153], v[164:165], v[162:163] op_sel_hi:[1,0,1]
	v_pk_mul_f32 v[164:165], v[100:101], v[154:155]
	v_pk_fma_f32 v[164:165], v[102:103], v[156:157], v[164:165]
	v_add_f32_e32 v159, v164, v165
	s_waitcnt lgkmcnt(2)
	v_pk_mul_f32 v[164:165], v[100:101], v[56:57]
	ds_read_b128 v[146:149], v93 offset:28928
	v_pk_fma_f32 v[164:165], v[102:103], v[58:59], v[164:165]
	ds_read_b128 v[142:145], v93 offset:28672
	v_add_f32_dpp v0, v97, v97 row_half_mirror row_mask:0xf bank_mask:0x5 bound_ctrl:1
	v_add_f32_e32 v164, v164, v165
	ds_read_b32 v158, v95 offset:1408
	ds_read_b128 v[136:139], v93 offset:28416
	v_add_f32_dpp v164, v164, v164 quad_perm:[1,0,3,2] row_mask:0xf bank_mask:0xf bound_ctrl:1
	v_pk_mul_f32 v[160:161], v[52:53], v[104:105] op_sel_hi:[1,0]
	v_pk_mul_f32 v[162:163], v[54:55], v[104:105] op_sel_hi:[1,0]
	v_add_f32_dpp v164, v164, v164 quad_perm:[2,3,0,1] row_mask:0xf bank_mask:0xf bound_ctrl:1
	v_pk_fma_f32 v[160:161], v[100:101], v[44:45], v[160:161]
	v_pk_fma_f32 v[162:163], v[102:103], v[46:47], v[162:163]
	v_add_f32_dpp v164, v164, v164 row_half_mirror row_mask:0xf bank_mask:0xf bound_ctrl:1
	ds_read_b128 v[150:153], v93 offset:29184
	ds_read_b128 v[154:157], v93 offset:28160
	v_add_f32_dpp v164, v164, v164 row_mirror row_mask:0xf bank_mask:0xf bound_ctrl:1
	s_waitcnt lgkmcnt(6)
	v_add_f32_dpp v0, v159, v159 row_half_mirror row_mask:0xf bank_mask:0xa bound_ctrl:1
	v_pk_fma_f32 v[100:101], v[48:49], v[164:165], v[160:161] op_sel_hi:[1,0,1]
	v_pk_fma_f32 v[102:103], v[50:51], v[164:165], v[162:163] op_sel_hi:[1,0,1]
	v_pk_mul_f32 v[164:165], v[100:101], v[40:41]
	v_pk_fma_f32 v[164:165], v[102:103], v[42:43], v[164:165]
	v_add_f32_e32 v97, v164, v165
	s_waitcnt lgkmcnt(2)
	v_pk_mul_f32 v[164:165], v[100:101], v[146:147]
	ds_read_b128 v[56:59], v93 offset:30208
	v_pk_fma_f32 v[164:165], v[102:103], v[148:149], v[164:165]
	ds_read_b128 v[52:55], v93 offset:29952
	v_add_f32_dpp v1, v97, v97 row_half_mirror row_mask:0xf bank_mask:0x5 bound_ctrl:1
	v_add_f32_e32 v164, v164, v165
	ds_read_b32 v104, v95 offset:1472
	ds_read_b128 v[44:47], v93 offset:29696
	v_add_f32_dpp v164, v164, v164 quad_perm:[1,0,3,2] row_mask:0xf bank_mask:0xf bound_ctrl:1
	v_pk_mul_f32 v[160:161], v[142:143], v[158:159] op_sel_hi:[1,0]
	v_pk_mul_f32 v[162:163], v[144:145], v[158:159] op_sel_hi:[1,0]
	v_add_f32_dpp v164, v164, v164 quad_perm:[2,3,0,1] row_mask:0xf bank_mask:0xf bound_ctrl:1
	v_pk_fma_f32 v[160:161], v[100:101], v[136:137], v[160:161]
	v_pk_fma_f32 v[162:163], v[102:103], v[138:139], v[162:163]
	v_add_f32_dpp v164, v164, v164 row_half_mirror row_mask:0xf bank_mask:0xf bound_ctrl:1
	ds_read_b128 v[48:51], v93 offset:30464
	ds_read_b128 v[40:43], v93 offset:29440
	v_add_f32_dpp v164, v164, v164 row_mirror row_mask:0xf bank_mask:0xf bound_ctrl:1
	s_waitcnt lgkmcnt(6)
; DEV void scan_phase(const Params& p, char* smem, const float* __restrict__ nx, const float* __restrict__ ng, u16* __restrict__ nh) {
;     ...
;         for (int s4 = 0; s4 < 8; ++s4) {
;           float yv[4];
; #pragma unroll
;           for (int u = 0; u < 4; ++u) {
;             const int step = s4 * 4 + u;
;             const float* o = ob + ((step + 1) & 31) * 320;
;             const float4 nr4 = *(const float4*)(o), nw4 = *(const float4*)(o + 64), nk4 = *(const float4*)(o + 128);
;             const float4 na4 = *(const float4*)(o + 192), nb4 = *(const float4*)(o + 256);
;             const float nv = vb[((step + 1) & 31) * 16];
;             __builtin_amdgcn_sched_barrier(0);
;             const f32x2 vv = {v, v};
;             f32x2 sa2 = s01 * f32x2{a4.x, a4.y};
;             sa2 = s23 * f32x2{a4.z, a4.w} + sa2;
;             float sa = sa2.x + sa2.y;
;             f32x2 t01 = s01 * f32x2{w4.x, w4.y};
;             f32x2 t23 = s23 * f32x2{w4.z, w4.w};
;             t01 = vv * f32x2{k4.x, k4.y} + t01;
;             t23 = vv * f32x2{k4.z, k4.w} + t23;
;             sa = reduce16(sa);
;             const f32x2 sav = {sa, sa};
;             s01 = sav * f32x2{b4.x, b4.y} + t01;
;             s23 = sav * f32x2{b4.z, b4.w} + t23;
;             f32x2 y2 = s01 * f32x2{r4.x, r4.y};
;             y2 = s23 * f32x2{r4.z, r4.w} + y2;
;             yv[u] = reduce16(y2.x + y2.y);
;             r4 = nr4; w4 = nw4; k4 = nk4; a4 = na4; b4 = nb4; v = nv;
;           }
;           *(float4*)(yb + s4 * 4) = float4{yv[0], yv[1], yv[2], yv[3]};
;         }
	v_pk_fma_f32 v[100:101], v[150:151], v[164:165], v[160:161] op_sel_hi:[1,0,1]
	v_pk_fma_f32 v[102:103], v[152:153], v[164:165], v[162:163] op_sel_hi:[1,0,1]
	v_pk_mul_f32 v[164:165], v[100:101], v[154:155]
	v_pk_fma_f32 v[164:165], v[102:103], v[156:157], v[164:165]
	v_add_f32_e32 v159, v164, v165
	s_nop 1
	v_add_f32_dpp v1, v159, v159 row_half_mirror row_mask:0xf bank_mask:0xa bound_ctrl:1
	s_waitcnt lgkmcnt(2)
	v_pk_mul_f32 v[164:165], v[100:101], v[56:57]
	ds_read_b128 v[146:149], v93 offset:31488
	v_pk_fma_f32 v[164:165], v[102:103], v[58:59], v[164:165]
	ds_read_b128 v[142:145], v93 offset:31232
	v_add_f32_dpp v0, v0, v0 row_ror:8 row_mask:0xf bank_mask:0x3 bound_ctrl:1
	v_add_f32_e32 v164, v164, v165
	ds_read_b32 v158, v95 offset:1536
	ds_read_b128 v[136:139], v93 offset:30976
	v_add_f32_dpp v164, v164, v164 quad_perm:[1,0,3,2] row_mask:0xf bank_mask:0xf bound_ctrl:1
	v_pk_mul_f32 v[160:161], v[52:53], v[104:105] op_sel_hi:[1,0]
	v_pk_mul_f32 v[162:163], v[54:55], v[104:105] op_sel_hi:[1,0]
	v_add_f32_dpp v164, v164, v164 quad_perm:[2,3,0,1] row_mask:0xf bank_mask:0xf bound_ctrl:1
	v_pk_fma_f32 v[160:161], v[100:101], v[44:45], v[160:161]
	v_pk_fma_f32 v[162:163], v[102:103], v[46:47], v[162:163]
	v_add_f32_dpp v164, v164, v164 row_half_mirror row_mask:0xf bank_mask:0xf bound_ctrl:1
	ds_read_b128 v[150:153], v93 offset:31744
	ds_read_b128 v[154:157], v93 offset:30720
	v_add_f32_dpp v164, v164, v164 row_mirror row_mask:0xf bank_mask:0xf bound_ctrl:1
	s_waitcnt lgkmcnt(6)
	v_add_f32_dpp v0, v1, v1 row_ror:8 row_mask:0xf bank_mask:0xc bound_ctrl:1
	v_pk_fma_f32 v[100:101], v[48:49], v[164:165], v[160:161] op_sel_hi:[1,0,1]
	v_pk_fma_f32 v[102:103], v[50:51], v[164:165], v[162:163] op_sel_hi:[1,0,1]
	v_add_f32_dpp v0, v0, v0 quad_perm:[1,0,3,2] row_mask:0xf bank_mask:0xf bound_ctrl:1
	v_pk_mul_f32 v[164:165], v[100:101], v[40:41]
	v_pk_fma_f32 v[164:165], v[102:103], v[42:43], v[164:165]
	v_add_f32_dpp v0, v0, v0 quad_perm:[2,3,0,1] row_mask:0xf bank_mask:0xf bound_ctrl:1
	v_add_f32_e32 v97, v164, v165
	s_waitcnt lgkmcnt(2)
	v_pk_mul_f32 v[164:165], v[100:101], v[146:147]
	ds_read_b128 v[56:59], v93 offset:32768
	v_pk_fma_f32 v[164:165], v[102:103], v[148:149], v[164:165]
	ds_read_b128 v[52:55], v93 offset:32512
	ds_write_b32 v91, v0 offset:80
	v_add_f32_e32 v164, v164, v165
	ds_read_b32 v104, v95 offset:1600
	ds_read_b128 v[44:47], v93 offset:32256
	v_add_f32_dpp v164, v164, v164 quad_perm:[1,0,3,2] row_mask:0xf bank_mask:0xf bound_ctrl:1
	v_pk_mul_f32 v[160:161], v[142:143], v[158:159] op_sel_hi:[1,0]
	v_pk_mul_f32 v[162:163], v[144:145], v[158:159] op_sel_hi:[1,0]
	v_add_f32_dpp v164, v164, v164 quad_perm:[2,3,0,1] row_mask:0xf bank_mask:0xf bound_ctrl:1
	v_pk_fma_f32 v[160:161], v[100:101], v[136:137], v[160:161]
	v_pk_fma_f32 v[162:163], v[102:103], v[138:139], v[162:163]
	v_add_f32_dpp v164, v164, v164 row_half_mirror row_mask:0xf bank_mask:0xf bound_ctrl:1
	ds_read_b128 v[48:51], v93 offset:33024
	ds_read_b128 v[40:43], v93 offset:32000
	v_add_f32_dpp v164, v164, v164 row_mirror row_mask:0xf bank_mask:0xf bound_ctrl:1
	s_waitcnt lgkmcnt(6)
	v_pk_fma_f32 v[100:101], v[150:151], v[164:165], v[160:161] op_sel_hi:[1,0,1]
	v_pk_fma_f32 v[102:103], v[152:153], v[164:165], v[162:163] op_sel_hi:[1,0,1]
	v_pk_mul_f32 v[164:165], v[100:101], v[154:155]
	v_pk_fma_f32 v[164:165], v[102:103], v[156:157], v[164:165]
	v_add_f32_e32 v159, v164, v165
	s_waitcnt lgkmcnt(2)
	v_pk_mul_f32 v[164:165], v[100:101], v[56:57]
	ds_read_b128 v[146:149], v93 offset:34048
	v_pk_fma_f32 v[164:165], v[102:103], v[58:59], v[164:165]
	ds_read_b128 v[142:145], v93 offset:33792
	v_add_f32_dpp v135, v97, v97 row_half_mirror row_mask:0xf bank_mask:0x5 bound_ctrl:1
	v_add_f32_e32 v164, v164, v165
	ds_read_b32 v158, v95 offset:1664
	ds_read_b128 v[136:139], v93 offset:33536
	v_add_f32_dpp v164, v164, v164 quad_perm:[1,0,3,2] row_mask:0xf bank_mask:0xf bound_ctrl:1
	v_pk_mul_f32 v[160:161], v[52:53], v[104:105] op_sel_hi:[1,0]
	v_pk_mul_f32 v[162:163], v[54:55], v[104:105] op_sel_hi:[1,0]
	v_add_f32_dpp v164, v164, v164 quad_perm:[2,3,0,1] row_mask:0xf bank_mask:0xf bound_ctrl:1
	v_pk_fma_f32 v[160:161], v[100:101], v[44:45], v[160:161]
	v_pk_fma_f32 v[162:163], v[102:103], v[46:47], v[162:163]
	v_add_f32_dpp v164, v164, v164 row_half_mirror row_mask:0xf bank_mask:0xf bound_ctrl:1
	ds_read_b128 v[150:153], v93 offset:34304
	ds_read_b128 v[154:157], v93 offset:33280
	v_add_f32_dpp v164, v164, v164 row_mirror row_mask:0xf bank_mask:0xf bound_ctrl:1
	s_waitcnt lgkmcnt(6)
	v_add_f32_dpp v135, v159, v159 row_half_mirror row_mask:0xf bank_mask:0xa bound_ctrl:1
	v_pk_fma_f32 v[100:101], v[48:49], v[164:165], v[160:161] op_sel_hi:[1,0,1]
	v_pk_fma_f32 v[102:103], v[50:51], v[164:165], v[162:163] op_sel_hi:[1,0,1]
	v_pk_mul_f32 v[164:165], v[100:101], v[40:41]
	v_pk_fma_f32 v[164:165], v[102:103], v[42:43], v[164:165]
	v_add_f32_e32 v97, v164, v165
	s_waitcnt lgkmcnt(2)
	v_pk_mul_f32 v[164:165], v[100:101], v[146:147]
	ds_read_b128 v[56:59], v93 offset:35328
	v_pk_fma_f32 v[164:165], v[102:103], v[148:149], v[164:165]
	ds_read_b128 v[52:55], v93 offset:35072
	v_add_f32_dpp v134, v97, v97 row_half_mirror row_mask:0xf bank_mask:0x5 bound_ctrl:1
	v_add_f32_e32 v164, v164, v165
	ds_read_b32 v104, v95 offset:1728
	ds_read_b128 v[44:47], v93 offset:34816
	v_add_f32_dpp v164, v164, v164 quad_perm:[1,0,3,2] row_mask:0xf bank_mask:0xf bound_ctrl:1
	v_pk_mul_f32 v[160:161], v[142:143], v[158:159] op_sel_hi:[1,0]
	v_pk_mul_f32 v[162:163], v[144:145], v[158:159] op_sel_hi:[1,0]
	v_add_f32_dpp v164, v164, v164 quad_perm:[2,3,0,1] row_mask:0xf bank_mask:0xf bound_ctrl:1
	v_pk_fma_f32 v[160:161], v[100:101], v[136:137], v[160:161]
	v_pk_fma_f32 v[162:163], v[102:103], v[138:139], v[162:163]
	v_add_f32_dpp v164, v164, v164 row_half_mirror row_mask:0xf bank_mask:0xf bound_ctrl:1
	ds_read_b128 v[48:51], v93 offset:35584
	ds_read_b128 v[40:43], v93 offset:34560
	v_add_f32_dpp v164, v164, v164 row_mirror row_mask:0xf bank_mask:0xf bound_ctrl:1
	s_waitcnt lgkmcnt(6)
; DEV void scan_phase(const Params& p, char* smem, const float* __restrict__ nx, const float* __restrict__ ng, u16* __restrict__ nh) {
;     ...
;         for (int s4 = 0; s4 < 8; ++s4) {
;           float yv[4];
; #pragma unroll
;           for (int u = 0; u < 4; ++u) {
;             const int step = s4 * 4 + u;
;             const float* o = ob + ((step + 1) & 31) * 320;
;             const float4 nr4 = *(const float4*)(o), nw4 = *(const float4*)(o + 64), nk4 = *(const float4*)(o + 128);
;             const float4 na4 = *(const float4*)(o + 192), nb4 = *(const float4*)(o + 256);
;             const float nv = vb[((step + 1) & 31) * 16];
;             __builtin_amdgcn_sched_barrier(0);
;             const f32x2 vv = {v, v};
;             f32x2 sa2 = s01 * f32x2{a4.x, a4.y};
;             sa2 = s23 * f32x2{a4.z, a4.w} + sa2;
;             float sa = sa2.x + sa2.y;
;             f32x2 t01 = s01 * f32x2{w4.x, w4.y};
;             f32x2 t23 = s23 * f32x2{w4.z, w4.w};
;             t01 = vv * f32x2{k4.x, k4.y} + t01;
;             t23 = vv * f32x2{k4.z, k4.w} + t23;
;             sa = reduce16(sa);
;             const f32x2 sav = {sa, sa};
;             s01 = sav * f32x2{b4.x, b4.y} + t01;
;             s23 = sav * f32x2{b4.z, b4.w} + t23;
;             f32x2 y2 = s01 * f32x2{r4.x, r4.y};
;             y2 = s23 * f32x2{r4.z, r4.w} + y2;
;             yv[u] = reduce16(y2.x + y2.y);
;             r4 = nr4; w4 = nw4; k4 = nk4; a4 = na4; b4 = nb4; v = nv;
;           }
;           *(float4*)(yb + s4 * 4) = float4{yv[0], yv[1], yv[2], yv[3]};
;         }
	v_pk_fma_f32 v[100:101], v[150:151], v[164:165], v[160:161] op_sel_hi:[1,0,1]
	v_pk_fma_f32 v[102:103], v[152:153], v[164:165], v[162:163] op_sel_hi:[1,0,1]
	v_pk_mul_f32 v[164:165], v[100:101], v[154:155]
	v_pk_fma_f32 v[164:165], v[102:103], v[156:157], v[164:165]
	v_add_f32_e32 v159, v164, v165
	s_nop 1
	v_add_f32_dpp v134, v159, v159 row_half_mirror row_mask:0xf bank_mask:0xa bound_ctrl:1
	s_waitcnt lgkmcnt(2)
	v_pk_mul_f32 v[164:165], v[100:101], v[56:57]
	ds_read_b128 v[146:149], v93 offset:36608
	v_pk_fma_f32 v[164:165], v[102:103], v[58:59], v[164:165]
	ds_read_b128 v[142:145], v93 offset:36352
	v_add_f32_dpp v135, v135, v135 row_ror:8 row_mask:0xf bank_mask:0x3 bound_ctrl:1
	v_add_f32_e32 v164, v164, v165
	ds_read_b32 v158, v95 offset:1792
	ds_read_b128 v[136:139], v93 offset:36096
	v_add_f32_dpp v164, v164, v164 quad_perm:[1,0,3,2] row_mask:0xf bank_mask:0xf bound_ctrl:1
	v_pk_mul_f32 v[160:161], v[52:53], v[104:105] op_sel_hi:[1,0]
	v_pk_mul_f32 v[162:163], v[54:55], v[104:105] op_sel_hi:[1,0]
	v_add_f32_dpp v164, v164, v164 quad_perm:[2,3,0,1] row_mask:0xf bank_mask:0xf bound_ctrl:1
	v_pk_fma_f32 v[160:161], v[100:101], v[44:45], v[160:161]
	v_pk_fma_f32 v[162:163], v[102:103], v[46:47], v[162:163]
	v_add_f32_dpp v164, v164, v164 row_half_mirror row_mask:0xf bank_mask:0xf bound_ctrl:1
	ds_read_b128 v[150:153], v93 offset:36864
	ds_read_b128 v[154:157], v93 offset:35840
	v_add_f32_dpp v164, v164, v164 row_mirror row_mask:0xf bank_mask:0xf bound_ctrl:1
	s_waitcnt lgkmcnt(6)
	v_add_f32_dpp v135, v134, v134 row_ror:8 row_mask:0xf bank_mask:0xc bound_ctrl:1
	v_pk_fma_f32 v[100:101], v[48:49], v[164:165], v[160:161] op_sel_hi:[1,0,1]
	v_pk_fma_f32 v[102:103], v[50:51], v[164:165], v[162:163] op_sel_hi:[1,0,1]
	v_add_f32_dpp v135, v135, v135 quad_perm:[1,0,3,2] row_mask:0xf bank_mask:0xf bound_ctrl:1
	v_pk_mul_f32 v[164:165], v[100:101], v[40:41]
	v_pk_fma_f32 v[164:165], v[102:103], v[42:43], v[164:165]
	v_add_f32_dpp v135, v135, v135 quad_perm:[2,3,0,1] row_mask:0xf bank_mask:0xf bound_ctrl:1
	v_add_f32_e32 v97, v164, v165
	s_waitcnt lgkmcnt(2)
	v_pk_mul_f32 v[164:165], v[100:101], v[146:147]
	ds_read_b128 v[56:59], v93 offset:37888
	v_pk_fma_f32 v[164:165], v[102:103], v[148:149], v[164:165]
	ds_read_b128 v[52:55], v93 offset:37632
	ds_write_b32 v91, v135 offset:96
	v_add_f32_e32 v164, v164, v165
	ds_read_b32 v104, v95 offset:1856
	ds_read_b128 v[44:47], v93 offset:37376
	v_add_f32_dpp v164, v164, v164 quad_perm:[1,0,3,2] row_mask:0xf bank_mask:0xf bound_ctrl:1
	v_pk_mul_f32 v[160:161], v[142:143], v[158:159] op_sel_hi:[1,0]
	v_pk_mul_f32 v[162:163], v[144:145], v[158:159] op_sel_hi:[1,0]
	v_add_f32_dpp v164, v164, v164 quad_perm:[2,3,0,1] row_mask:0xf bank_mask:0xf bound_ctrl:1
	v_pk_fma_f32 v[160:161], v[100:101], v[136:137], v[160:161]
	v_pk_fma_f32 v[162:163], v[102:103], v[138:139], v[162:163]
	v_add_f32_dpp v164, v164, v164 row_half_mirror row_mask:0xf bank_mask:0xf bound_ctrl:1
	ds_read_b128 v[48:51], v93 offset:38144
	ds_read_b128 v[40:43], v93 offset:37120
	v_add_f32_dpp v164, v164, v164 row_mirror row_mask:0xf bank_mask:0xf bound_ctrl:1
	s_waitcnt lgkmcnt(6)
	v_pk_fma_f32 v[100:101], v[150:151], v[164:165], v[160:161] op_sel_hi:[1,0,1]
	v_pk_fma_f32 v[102:103], v[152:153], v[164:165], v[162:163] op_sel_hi:[1,0,1]
	v_pk_mul_f32 v[164:165], v[100:101], v[154:155]
	v_pk_fma_f32 v[164:165], v[102:103], v[156:157], v[164:165]
	v_add_f32_e32 v159, v164, v165
	s_waitcnt lgkmcnt(2)
	v_pk_mul_f32 v[164:165], v[100:101], v[56:57]
	ds_read_b128 v[146:149], v93 offset:39168
	v_pk_fma_f32 v[164:165], v[102:103], v[58:59], v[164:165]
	ds_read_b128 v[142:145], v93 offset:38912
	v_add_f32_dpp v0, v97, v97 row_half_mirror row_mask:0xf bank_mask:0x5 bound_ctrl:1
	v_add_f32_e32 v164, v164, v165
	ds_read_b32 v158, v95 offset:1920
	ds_read_b128 v[136:139], v93 offset:38656
	v_add_f32_dpp v164, v164, v164 quad_perm:[1,0,3,2] row_mask:0xf bank_mask:0xf bound_ctrl:1
	v_pk_mul_f32 v[160:161], v[52:53], v[104:105] op_sel_hi:[1,0]
	v_pk_mul_f32 v[162:163], v[54:55], v[104:105] op_sel_hi:[1,0]
	v_add_f32_dpp v164, v164, v164 quad_perm:[2,3,0,1] row_mask:0xf bank_mask:0xf bound_ctrl:1
	v_pk_fma_f32 v[160:161], v[100:101], v[44:45], v[160:161]
	v_pk_fma_f32 v[162:163], v[102:103], v[46:47], v[162:163]
	v_add_f32_dpp v164, v164, v164 row_half_mirror row_mask:0xf bank_mask:0xf bound_ctrl:1
	ds_read_b128 v[150:153], v93 offset:39424
	ds_read_b128 v[154:157], v93 offset:38400
	v_add_f32_dpp v164, v164, v164 row_mirror row_mask:0xf bank_mask:0xf bound_ctrl:1
	s_waitcnt lgkmcnt(6)
	v_add_f32_dpp v0, v159, v159 row_half_mirror row_mask:0xf bank_mask:0xa bound_ctrl:1
	v_pk_fma_f32 v[100:101], v[48:49], v[164:165], v[160:161] op_sel_hi:[1,0,1]
	v_pk_fma_f32 v[102:103], v[50:51], v[164:165], v[162:163] op_sel_hi:[1,0,1]
	v_pk_mul_f32 v[164:165], v[100:101], v[40:41]
	v_pk_fma_f32 v[164:165], v[102:103], v[42:43], v[164:165]
	v_add_f32_e32 v97, v164, v165
	s_waitcnt lgkmcnt(2)
	v_pk_mul_f32 v[164:165], v[100:101], v[146:147]
	ds_read_b128 v[56:59], v93 offset:40448
	v_pk_fma_f32 v[164:165], v[102:103], v[148:149], v[164:165]
	ds_read_b128 v[52:55], v93 offset:40192
	v_add_f32_dpp v1, v97, v97 row_half_mirror row_mask:0xf bank_mask:0x5 bound_ctrl:1
	v_add_f32_e32 v164, v164, v165
	ds_read_b32 v104, v95 offset:1984
	ds_read_b128 v[44:47], v93 offset:39936
	v_add_f32_dpp v164, v164, v164 quad_perm:[1,0,3,2] row_mask:0xf bank_mask:0xf bound_ctrl:1
	v_pk_mul_f32 v[160:161], v[142:143], v[158:159] op_sel_hi:[1,0]
	v_pk_mul_f32 v[162:163], v[144:145], v[158:159] op_sel_hi:[1,0]
	v_add_f32_dpp v164, v164, v164 quad_perm:[2,3,0,1] row_mask:0xf bank_mask:0xf bound_ctrl:1
	v_pk_fma_f32 v[160:161], v[100:101], v[136:137], v[160:161]
	v_pk_fma_f32 v[162:163], v[102:103], v[138:139], v[162:163]
	v_add_f32_dpp v164, v164, v164 row_half_mirror row_mask:0xf bank_mask:0xf bound_ctrl:1
	ds_read_b128 v[48:51], v93 offset:40704
	ds_read_b128 v[40:43], v93 offset:39680
	v_add_f32_dpp v164, v164, v164 row_mirror row_mask:0xf bank_mask:0xf bound_ctrl:1
	s_waitcnt lgkmcnt(6)
	v_pk_fma_f32 v[100:101], v[150:151], v[164:165], v[160:161] op_sel_hi:[1,0,1]
	v_pk_fma_f32 v[102:103], v[152:153], v[164:165], v[162:163] op_sel_hi:[1,0,1]
	v_pk_mul_f32 v[164:165], v[100:101], v[154:155]
	v_pk_fma_f32 v[164:165], v[102:103], v[156:157], v[164:165]
	v_add_f32_e32 v159, v164, v165
	s_nop 1
	v_add_f32_dpp v1, v159, v159 row_half_mirror row_mask:0xf bank_mask:0xa bound_ctrl:1
	v_add_f32_dpp v0, v0, v0 row_ror:8 row_mask:0xf bank_mask:0x3 bound_ctrl:1
	s_nop 0
	v_add_f32_dpp v0, v1, v1 row_ror:8 row_mask:0xf bank_mask:0xc bound_ctrl:1
	s_nop 1
	v_add_f32_dpp v0, v0, v0 quad_perm:[1,0,3,2] row_mask:0xf bank_mask:0xf bound_ctrl:1
	s_nop 1
	v_add_f32_dpp v0, v0, v0 quad_perm:[2,3,0,1] row_mask:0xf bank_mask:0xf bound_ctrl:1
	ds_write_b32 v91, v0 offset:112
	s_branch .LBB0_644
